# FoX: packed f32 fma (scale+bias of scores) split into scalar v_fma pairs
# speedup vs baseline: 1.0034x; 1.0009x over previous
; __device__ __forceinline__ f32x16 mfma32(bf16x8 a, bf16x8 b, f32x16 c) { return __builtin_amdgcn_mfma_f32_32x32x16_bf16(a, b, c, 0, 0, 0); }
; template <int MODE> ...
;     ...
;         const lptr Kt = L + A_KT + buf * 9216, Vt = L + A_VT + vcur * 12288;
;         f32x16 s0, s1;
; #pragma unroll
;         for (int s4 = 0; s4 < 4; ++s4) {
;             const bf16x8 a0 = lds_ld<bf16x8>(Kt + n * KP + s4 * 32 + hl * 16);
;             const bf16x8 a1 = lds_ld<bf16x8>(Kt + (32 + n) * KP + s4 * 32 + hl * 16);
;             if (s4 == 0) { s0 = mfma32(a0, qf[0], negm); s1 = mfma32(a1, qf[0], negm); }
;             else { s0 = mfma32(a0, qf[s4], s0); s1 = mfma32(a1, qf[s4], s1); }
;         }
;         const int kbase = 64 * kt + 4 * hl;
;         const bool far = (MODE == MODE_WIN || MODE == MODE_SEL) ? (wtmin - (64 * kt + 63) >= 128) : false;
;         const bool fmask = (MODE == MODE_FOX) ? (64 * kt + 63 > wtmin) : false;
;         const bool clean = (MODE == MODE_WIN) ? (far && (wtmax - 64 * kt < W)) : false;
;         const float mref = (MODE == MODE_CMP2) ? mfix : ((m == -INFINITY) ? 0.f : m);
;         if (MODE == MODE_FOX) {
; #pragma unroll
;             for (int kb = 0; kb < 2; ++kb)
; #pragma unroll
;                 for (int a = 0; a < 4; ++a) {
;                     const f32x4 c4 = lds_ld<f32x4>(L + A_CB + buf * 256 + (32 * kb + 8 * a + 4 * hl) * 4);
; #pragma unroll
;                     for (int e = 0; e < 4; ++e) { const int r = 4 * a + e; if (kb) s1[r] = s1[r] * SC2 + c4[e]; else s0[r] = s0[r] * SC2 + c4[e]; }
;                 }
;             if (__builtin_amdgcn_readfirstlane((int)fmask)) {
; #pragma unroll
;                 for (int r = 0; r < 16; ++r) {
;                     const int key = kbase + 8 * (r >> 2) + (r & 3);
;                     if (key > t) s0[r] = -INFINITY;
;                     if (key + 32 > t) s1[r] = -INFINITY;
;                 }
;             }
.LBB0_178:
	v_add_u32_e32 v14, v134, v135
	v_add_u32_e32 v0, v136, v135
	v_add_u32_e32 v156, v138, v139
	ds_read_b128 v[170:173], v14 offset:0
	ds_read_b128 v[174:177], v0 offset:0
	ds_read_b128 v[178:181], v14 offset:32
	ds_read_b128 v[182:185], v0 offset:32
	ds_read_b128 v[186:189], v14 offset:64
	ds_read_b128 v[194:197], v0 offset:64
	ds_read_b128 v[198:201], v14 offset:96
	ds_read_b128 v[202:205], v0 offset:96
	s_or_b32 s1, s0, 63
	v_cmp_gt_i32_e32 vcc, s1, v125
	s_waitcnt lgkmcnt(7)
	v_mfma_f32_32x32x16_bf16 v[80:95], v[170:173], v[104:107], v[48:63]
	ds_read_b64_tr_b16 v[206:207], v156 offset:18432
	ds_read_b64_tr_b16 v[208:209], v156 offset:19968
	s_waitcnt lgkmcnt(8)
	v_mfma_f32_32x32x16_bf16 v[64:79], v[174:177], v[104:107], v[48:63]
	ds_read_b64_tr_b16 v[210:211], v156 offset:21504
	ds_read_b64_tr_b16 v[212:213], v156 offset:23040
	s_waitcnt lgkmcnt(9)
	v_mfma_f32_32x32x16_bf16 v[80:95], v[178:181], v[96:99], v[80:95]
	ds_read_b64_tr_b16 v[226:227], v156 offset:24576
	ds_read_b64_tr_b16 v[228:229], v156 offset:26112
	s_waitcnt lgkmcnt(10)
	v_mfma_f32_32x32x16_bf16 v[64:79], v[182:185], v[96:99], v[64:79]
	ds_read_b64_tr_b16 v[230:231], v156 offset:27648
	ds_read_b64_tr_b16 v[232:233], v156 offset:29184
	s_waitcnt lgkmcnt(11)
	v_mfma_f32_32x32x16_bf16 v[80:95], v[186:189], v[100:103], v[80:95]
	ds_read_b64_tr_b16 v[234:235], v156 offset:18496
	ds_read_b64_tr_b16 v[236:237], v156 offset:20032
	s_waitcnt lgkmcnt(12)
	v_mfma_f32_32x32x16_bf16 v[64:79], v[194:197], v[100:103], v[64:79]
	ds_read_b64_tr_b16 v[238:239], v156 offset:21568
	ds_read_b64_tr_b16 v[240:241], v156 offset:23104
	v_cndmask_b32_e64 v0, 0, 1, vcc
	s_nop 0
	v_readfirstlane_b32 s1, v0
	s_bitcmp0_b32 s1, 0
	s_waitcnt lgkmcnt(13)
	v_mfma_f32_32x32x16_bf16 v[80:95], v[198:201], v[108:111], v[80:95]
	ds_read_b64_tr_b16 v[242:243], v156 offset:24640
	ds_read_b64_tr_b16 v[244:245], v156 offset:26176
	s_waitcnt lgkmcnt(14)
	v_mfma_f32_32x32x16_bf16 v[64:79], v[202:205], v[108:111], v[64:79]
	ds_read_b64_tr_b16 v[246:247], v156 offset:27712
	ds_read_b64_tr_b16 v[248:249], v156 offset:29248
	ds_read_b128 v[144:147], v135 offset:43008
	ds_read_b128 v[148:151], v135 offset:43040
	ds_read_b128 v[152:155], v135 offset:43072
	ds_read_b128 v[12:15], v135 offset:43104
	s_waitcnt lgkmcnt(3)
	s_nop 5
	v_fma_f32 v82, v82, s54, v146
	v_fma_f32 v83, v83, s54, v147
	s_waitcnt lgkmcnt(2)
	v_fma_f32 v86, v86, s54, v150
	v_fma_f32 v87, v87, s54, v151
	s_waitcnt lgkmcnt(1)
	v_fma_f32 v88, v88, s54, v152
	v_fma_f32 v89, v89, s54, v153
	s_waitcnt lgkmcnt(0)
	v_fma_f32 v10, v94, s54, v14
	v_fma_f32 v11, v95, s54, v15
	v_fma_f32 v12, v92, s54, v12
	v_fma_f32 v13, v93, s54, v13
	v_fma_f32 v14, v90, s54, v154
	v_fma_f32 v15, v91, s54, v155
	v_fma_f32 v84, v84, s54, v148
	v_fma_f32 v85, v85, s54, v149
	v_fma_f32 v80, v80, s54, v144
	v_fma_f32 v81, v81, s54, v145
	ds_read_b128 v[90:93], v135 offset:43136
	ds_read_b128 v[144:147], v135 offset:43168
	ds_read_b128 v[148:151], v135 offset:43200
	ds_read_b128 v[152:155], v135 offset:43232
	s_waitcnt lgkmcnt(3)
	v_fma_f32 v66, v66, s54, v92
	v_fma_f32 v67, v67, s54, v93
	s_waitcnt lgkmcnt(2)
	v_fma_f32 v70, v70, s54, v146
	v_fma_f32 v71, v71, s54, v147
	s_waitcnt lgkmcnt(1)
	v_fma_f32 v74, v74, s54, v150
	v_fma_f32 v75, v75, s54, v151
	s_waitcnt lgkmcnt(0)
	v_fma_f32 v78, v78, s54, v154
	v_fma_f32 v79, v79, s54, v155
	v_fma_f32 v76, v76, s54, v152
	v_fma_f32 v77, v77, s54, v153
	v_fma_f32 v72, v72, s54, v148
	v_fma_f32 v73, v73, s54, v149
	v_fma_f32 v68, v68, s54, v144
	v_fma_f32 v69, v69, s54, v145
	v_fma_f32 v64, v64, s54, v90
	v_fma_f32 v65, v65, s54, v91
	s_cbranch_scc1 .LBB0_180
	v_or_b32_e32 v0, s0, v137
	v_or_b32_e32 v90, 32, v0
	v_cmp_le_i32_e32 vcc, v90, v126
	v_or_b32_e32 v90, 33, v0
	s_nop 0
	v_cndmask_b32_e32 v64, v220, v64, vcc
	v_cmp_lt_i32_e32 vcc, v0, v126
	s_nop 1
	v_cndmask_b32_e32 v81, v220, v81, vcc
	v_cmp_le_i32_e32 vcc, v0, v126
	s_nop 1
	v_cndmask_b32_e32 v80, v220, v80, vcc
	v_cmp_le_i32_e32 vcc, v90, v126
	v_or_b32_e32 v90, 2, v0
	s_nop 0
	v_cndmask_b32_e32 v65, v220, v65, vcc
	v_cmp_le_i32_e32 vcc, v90, v126
	v_or_b32_e32 v90, 34, v0
	s_nop 0
	v_cndmask_b32_e32 v82, v220, v82, vcc
	v_cmp_le_i32_e32 vcc, v90, v126
	v_or_b32_e32 v90, 3, v0
	s_nop 0
	v_cndmask_b32_e32 v66, v220, v66, vcc
	v_cmp_le_i32_e32 vcc, v90, v126
	v_or_b32_e32 v90, 35, v0
	s_nop 0
	v_cndmask_b32_e32 v83, v220, v83, vcc
	v_cmp_le_i32_e32 vcc, v90, v126
	v_or_b32_e32 v90, 8, v0
	s_nop 0
	v_cndmask_b32_e32 v67, v220, v67, vcc
	v_cmp_le_i32_e32 vcc, v90, v126
	v_or_b32_e32 v90, 40, v0
	s_nop 0
	v_cndmask_b32_e32 v84, v220, v84, vcc
	v_cmp_le_i32_e32 vcc, v90, v126
	v_or_b32_e32 v90, 9, v0
	s_nop 0
	v_cndmask_b32_e32 v68, v220, v68, vcc
	v_cmp_le_i32_e32 vcc, v90, v126
	v_or_b32_e32 v90, 41, v0
	s_nop 0
	v_cndmask_b32_e32 v85, v220, v85, vcc
	v_cmp_le_i32_e32 vcc, v90, v126
	v_or_b32_e32 v90, 10, v0
	s_nop 0
	v_cndmask_b32_e32 v69, v220, v69, vcc
	v_cmp_le_i32_e32 vcc, v90, v126
	v_or_b32_e32 v90, 42, v0
	s_nop 0
	v_cndmask_b32_e32 v86, v220, v86, vcc
	v_cmp_le_i32_e32 vcc, v90, v126
	v_or_b32_e32 v90, 11, v0
	s_nop 0
	v_cndmask_b32_e32 v70, v220, v70, vcc
	v_cmp_le_i32_e32 vcc, v90, v126
	v_or_b32_e32 v90, 43, v0
	s_nop 0
	v_cndmask_b32_e32 v87, v220, v87, vcc
	v_cmp_le_i32_e32 vcc, v90, v126
	v_or_b32_e32 v90, 16, v0
	s_nop 0
	v_cndmask_b32_e32 v71, v220, v71, vcc
	v_cmp_le_i32_e32 vcc, v90, v126
	v_or_b32_e32 v90, 48, v0
	s_nop 0
	v_cndmask_b32_e32 v88, v220, v88, vcc
	v_cmp_le_i32_e32 vcc, v90, v126
	v_or_b32_e32 v90, 17, v0
	s_nop 0
	v_cndmask_b32_e32 v72, v220, v72, vcc
	v_cmp_le_i32_e32 vcc, v90, v126
	v_or_b32_e32 v90, 49, v0
	s_nop 0
	v_cndmask_b32_e32 v89, v220, v89, vcc
	v_cmp_le_i32_e32 vcc, v90, v126
	v_or_b32_e32 v90, 18, v0
	s_nop 0
	v_cndmask_b32_e32 v73, v220, v73, vcc
	v_cmp_le_i32_e32 vcc, v90, v126
	v_or_b32_e32 v90, 50, v0
	s_nop 0
	v_cndmask_b32_e32 v14, v220, v14, vcc
	v_cmp_le_i32_e32 vcc, v90, v126
	v_or_b32_e32 v90, 19, v0
	s_nop 0
	v_cndmask_b32_e32 v74, v220, v74, vcc
	v_cmp_le_i32_e32 vcc, v90, v126
	v_or_b32_e32 v90, 51, v0
	s_nop 0
	v_cndmask_b32_e32 v15, v220, v15, vcc
	v_cmp_le_i32_e32 vcc, v90, v126
	v_or_b32_e32 v90, 24, v0
	s_nop 0
	v_cndmask_b32_e32 v75, v220, v75, vcc
	v_cmp_le_i32_e32 vcc, v90, v126
	v_or_b32_e32 v90, 56, v0
	s_nop 0
	v_cndmask_b32_e32 v12, v220, v12, vcc
	v_cmp_le_i32_e32 vcc, v90, v126
	v_or_b32_e32 v90, 25, v0
	s_nop 0
	v_cndmask_b32_e32 v76, v220, v76, vcc
	v_cmp_le_i32_e32 vcc, v90, v126
	v_or_b32_e32 v90, 57, v0
	s_nop 0
	v_cndmask_b32_e32 v13, v220, v13, vcc
	v_cmp_le_i32_e32 vcc, v90, v126
	v_or_b32_e32 v90, 26, v0
	s_nop 0
	v_cndmask_b32_e32 v77, v220, v77, vcc
	v_cmp_le_i32_e32 vcc, v90, v126
	v_or_b32_e32 v90, 58, v0
	s_nop 0
	v_cndmask_b32_e32 v10, v220, v10, vcc
	v_cmp_le_i32_e32 vcc, v90, v126
	v_or_b32_e32 v90, 27, v0
	v_or_b32_e32 v0, 59, v0
	v_cndmask_b32_e32 v78, v220, v78, vcc
	v_cmp_le_i32_e32 vcc, v90, v126
	s_nop 1
	v_cndmask_b32_e32 v11, v220, v11, vcc
	v_cmp_le_i32_e32 vcc, v0, v126
	s_nop 1
	v_cndmask_b32_e32 v79, v220, v79, vcc

; __device__ __forceinline__ f32x16 mfma32(bf16x8 a, bf16x8 b, f32x16 c) { return __builtin_amdgcn_mfma_f32_32x32x16_bf16(a, b, c, 0, 0, 0); }
; template <int MODE> ...
;     ...
;         const lptr Kt = L + A_KT + buf * 9216, Vt = L + A_VT + vcur * 12288;
;         f32x16 s0, s1;
; #pragma unroll
;         for (int s4 = 0; s4 < 4; ++s4) {
;             const bf16x8 a0 = lds_ld<bf16x8>(Kt + n * KP + s4 * 32 + hl * 16);
;             const bf16x8 a1 = lds_ld<bf16x8>(Kt + (32 + n) * KP + s4 * 32 + hl * 16);
;             if (s4 == 0) { s0 = mfma32(a0, qf[0], negm); s1 = mfma32(a1, qf[0], negm); }
;             else { s0 = mfma32(a0, qf[s4], s0); s1 = mfma32(a1, qf[s4], s1); }
;         }
;         const int kbase = 64 * kt + 4 * hl;
;         const bool far = (MODE == MODE_WIN || MODE == MODE_SEL) ? (wtmin - (64 * kt + 63) >= 128) : false;
;         const bool fmask = (MODE == MODE_FOX) ? (64 * kt + 63 > wtmin) : false;
;         const bool clean = (MODE == MODE_WIN) ? (far && (wtmax - 64 * kt < W)) : false;
;         const float mref = (MODE == MODE_CMP2) ? mfix : ((m == -INFINITY) ? 0.f : m);
;         if (MODE == MODE_FOX) {
; #pragma unroll
;             for (int kb = 0; kb < 2; ++kb)
; #pragma unroll
;                 for (int a = 0; a < 4; ++a) {
;                     const f32x4 c4 = lds_ld<f32x4>(L + A_CB + buf * 256 + (32 * kb + 8 * a + 4 * hl) * 4);
; #pragma unroll
;                     for (int e = 0; e < 4; ++e) { const int r = 4 * a + e; if (kb) s1[r] = s1[r] * SC2 + c4[e]; else s0[r] = s0[r] * SC2 + c4[e]; }
;                 }
;             if (__builtin_amdgcn_readfirstlane((int)fmask)) {
; #pragma unroll
;                 for (int r = 0; r < 16; ++r) {
;                     const int key = kbase + 8 * (r >> 2) + (r & 3);
;                     if (key > t) s0[r] = -INFINITY;
;                     if (key + 32 > t) s1[r] = -INFINITY;
;                 }
;             }
.LBB0_194:
	v_add_u32_e32 v14, v134, v135
	v_add_u32_e32 v0, v136, v135
	v_add_u32_e32 v156, v138, v139
	ds_read_b128 v[170:173], v14 offset:9216
	ds_read_b128 v[174:177], v0 offset:9216
	ds_read_b128 v[178:181], v14 offset:9248
	ds_read_b128 v[182:185], v0 offset:9248
	ds_read_b128 v[186:189], v14 offset:9280
	ds_read_b128 v[194:197], v0 offset:9280
	ds_read_b128 v[198:201], v14 offset:9312
	ds_read_b128 v[202:205], v0 offset:9312
	s_or_b32 s1, s0, 63
	v_cmp_gt_i32_e32 vcc, s1, v125
	s_waitcnt lgkmcnt(7)
	v_mfma_f32_32x32x16_bf16 v[80:95], v[170:173], v[104:107], v[48:63]
	ds_read_b64_tr_b16 v[206:207], v156 offset:30720
	ds_read_b64_tr_b16 v[208:209], v156 offset:32256
	s_waitcnt lgkmcnt(8)
	v_mfma_f32_32x32x16_bf16 v[64:79], v[174:177], v[104:107], v[48:63]
	ds_read_b64_tr_b16 v[210:211], v156 offset:33792
	ds_read_b64_tr_b16 v[212:213], v156 offset:35328
	s_waitcnt lgkmcnt(9)
	v_mfma_f32_32x32x16_bf16 v[80:95], v[178:181], v[96:99], v[80:95]
	ds_read_b64_tr_b16 v[226:227], v156 offset:36864
	ds_read_b64_tr_b16 v[228:229], v156 offset:38400
	s_waitcnt lgkmcnt(10)
	v_mfma_f32_32x32x16_bf16 v[64:79], v[182:185], v[96:99], v[64:79]
	ds_read_b64_tr_b16 v[230:231], v156 offset:39936
	ds_read_b64_tr_b16 v[232:233], v156 offset:41472
	s_waitcnt lgkmcnt(11)
	v_mfma_f32_32x32x16_bf16 v[80:95], v[186:189], v[100:103], v[80:95]
	ds_read_b64_tr_b16 v[234:235], v156 offset:30784
	ds_read_b64_tr_b16 v[236:237], v156 offset:32320
	s_waitcnt lgkmcnt(12)
	v_mfma_f32_32x32x16_bf16 v[64:79], v[194:197], v[100:103], v[64:79]
	ds_read_b64_tr_b16 v[238:239], v156 offset:33856
	ds_read_b64_tr_b16 v[240:241], v156 offset:35392
	v_cndmask_b32_e64 v0, 0, 1, vcc
	s_nop 0
	v_readfirstlane_b32 s1, v0
	s_bitcmp0_b32 s1, 0
	s_waitcnt lgkmcnt(13)
	v_mfma_f32_32x32x16_bf16 v[80:95], v[198:201], v[108:111], v[80:95]
	ds_read_b64_tr_b16 v[242:243], v156 offset:36928
	ds_read_b64_tr_b16 v[244:245], v156 offset:38464
	s_waitcnt lgkmcnt(14)
	v_mfma_f32_32x32x16_bf16 v[64:79], v[202:205], v[108:111], v[64:79]
	ds_read_b64_tr_b16 v[246:247], v156 offset:40000
	ds_read_b64_tr_b16 v[248:249], v156 offset:41536
	ds_read_b128 v[144:147], v135 offset:43264
	ds_read_b128 v[148:151], v135 offset:43296
	ds_read_b128 v[152:155], v135 offset:43328
	ds_read_b128 v[12:15], v135 offset:43360
	s_waitcnt lgkmcnt(3)
	s_nop 5
	v_fma_f32 v82, v82, s54, v146
	v_fma_f32 v83, v83, s54, v147
	s_waitcnt lgkmcnt(2)
	v_fma_f32 v86, v86, s54, v150
	v_fma_f32 v87, v87, s54, v151
	s_waitcnt lgkmcnt(1)
	v_fma_f32 v88, v88, s54, v152
	v_fma_f32 v89, v89, s54, v153
	s_waitcnt lgkmcnt(0)
	v_fma_f32 v10, v94, s54, v14
	v_fma_f32 v11, v95, s54, v15
	v_fma_f32 v12, v92, s54, v12
	v_fma_f32 v13, v93, s54, v13
	v_fma_f32 v14, v90, s54, v154
	v_fma_f32 v15, v91, s54, v155
	v_fma_f32 v84, v84, s54, v148
	v_fma_f32 v85, v85, s54, v149
	v_fma_f32 v80, v80, s54, v144
	v_fma_f32 v81, v81, s54, v145
	ds_read_b128 v[90:93], v135 offset:43392
	ds_read_b128 v[144:147], v135 offset:43424
	ds_read_b128 v[148:151], v135 offset:43456
	ds_read_b128 v[152:155], v135 offset:43488
	s_waitcnt lgkmcnt(3)
	v_fma_f32 v66, v66, s54, v92
	v_fma_f32 v67, v67, s54, v93
	s_waitcnt lgkmcnt(2)
	v_fma_f32 v70, v70, s54, v146
	v_fma_f32 v71, v71, s54, v147
	s_waitcnt lgkmcnt(1)
	v_fma_f32 v74, v74, s54, v150
	v_fma_f32 v75, v75, s54, v151
	s_waitcnt lgkmcnt(0)
	v_fma_f32 v78, v78, s54, v154
	v_fma_f32 v79, v79, s54, v155
	v_fma_f32 v76, v76, s54, v152
	v_fma_f32 v77, v77, s54, v153
	v_fma_f32 v72, v72, s54, v148
	v_fma_f32 v73, v73, s54, v149
	v_fma_f32 v68, v68, s54, v144
	v_fma_f32 v69, v69, s54, v145
	v_fma_f32 v64, v64, s54, v90
	v_fma_f32 v65, v65, s54, v91
	s_cbranch_scc1 .LBB0_196
	v_or_b32_e32 v0, s0, v137
	v_or_b32_e32 v90, 32, v0
	v_cmp_le_i32_e32 vcc, v90, v126
	v_or_b32_e32 v90, 33, v0
	s_nop 0
	v_cndmask_b32_e32 v64, v220, v64, vcc
	v_cmp_lt_i32_e32 vcc, v0, v126
	s_nop 1
	v_cndmask_b32_e32 v81, v220, v81, vcc
	v_cmp_le_i32_e32 vcc, v0, v126
	s_nop 1
	v_cndmask_b32_e32 v80, v220, v80, vcc
	v_cmp_le_i32_e32 vcc, v90, v126
	v_or_b32_e32 v90, 2, v0
	s_nop 0
	v_cndmask_b32_e32 v65, v220, v65, vcc
	v_cmp_le_i32_e32 vcc, v90, v126
	v_or_b32_e32 v90, 34, v0
	s_nop 0
	v_cndmask_b32_e32 v82, v220, v82, vcc
	v_cmp_le_i32_e32 vcc, v90, v126
	v_or_b32_e32 v90, 3, v0
	s_nop 0
	v_cndmask_b32_e32 v66, v220, v66, vcc
	v_cmp_le_i32_e32 vcc, v90, v126
	v_or_b32_e32 v90, 35, v0
	s_nop 0
	v_cndmask_b32_e32 v83, v220, v83, vcc
	v_cmp_le_i32_e32 vcc, v90, v126
	v_or_b32_e32 v90, 8, v0
	s_nop 0
	v_cndmask_b32_e32 v67, v220, v67, vcc
	v_cmp_le_i32_e32 vcc, v90, v126
	v_or_b32_e32 v90, 40, v0
	s_nop 0
	v_cndmask_b32_e32 v84, v220, v84, vcc
	v_cmp_le_i32_e32 vcc, v90, v126
	v_or_b32_e32 v90, 9, v0
	s_nop 0
	v_cndmask_b32_e32 v68, v220, v68, vcc
	v_cmp_le_i32_e32 vcc, v90, v126
	v_or_b32_e32 v90, 41, v0
	s_nop 0
	v_cndmask_b32_e32 v85, v220, v85, vcc
	v_cmp_le_i32_e32 vcc, v90, v126
	v_or_b32_e32 v90, 10, v0
	s_nop 0
	v_cndmask_b32_e32 v69, v220, v69, vcc
	v_cmp_le_i32_e32 vcc, v90, v126
	v_or_b32_e32 v90, 42, v0
	s_nop 0
	v_cndmask_b32_e32 v86, v220, v86, vcc
	v_cmp_le_i32_e32 vcc, v90, v126
	v_or_b32_e32 v90, 11, v0
	s_nop 0
	v_cndmask_b32_e32 v70, v220, v70, vcc
	v_cmp_le_i32_e32 vcc, v90, v126
	v_or_b32_e32 v90, 43, v0
	s_nop 0
	v_cndmask_b32_e32 v87, v220, v87, vcc
	v_cmp_le_i32_e32 vcc, v90, v126
	v_or_b32_e32 v90, 16, v0
	s_nop 0
	v_cndmask_b32_e32 v71, v220, v71, vcc
	v_cmp_le_i32_e32 vcc, v90, v126
	v_or_b32_e32 v90, 48, v0
	s_nop 0
	v_cndmask_b32_e32 v88, v220, v88, vcc
	v_cmp_le_i32_e32 vcc, v90, v126
	v_or_b32_e32 v90, 17, v0
	s_nop 0
	v_cndmask_b32_e32 v72, v220, v72, vcc
	v_cmp_le_i32_e32 vcc, v90, v126
	v_or_b32_e32 v90, 49, v0
	s_nop 0
	v_cndmask_b32_e32 v89, v220, v89, vcc
	v_cmp_le_i32_e32 vcc, v90, v126
	v_or_b32_e32 v90, 18, v0
	s_nop 0
	v_cndmask_b32_e32 v73, v220, v73, vcc
	v_cmp_le_i32_e32 vcc, v90, v126
	v_or_b32_e32 v90, 50, v0
	s_nop 0
	v_cndmask_b32_e32 v14, v220, v14, vcc
	v_cmp_le_i32_e32 vcc, v90, v126
	v_or_b32_e32 v90, 19, v0
	s_nop 0
	v_cndmask_b32_e32 v74, v220, v74, vcc
	v_cmp_le_i32_e32 vcc, v90, v126
	v_or_b32_e32 v90, 51, v0
	s_nop 0
	v_cndmask_b32_e32 v15, v220, v15, vcc
	v_cmp_le_i32_e32 vcc, v90, v126
	v_or_b32_e32 v90, 24, v0
	s_nop 0
	v_cndmask_b32_e32 v75, v220, v75, vcc
	v_cmp_le_i32_e32 vcc, v90, v126
	v_or_b32_e32 v90, 56, v0
	s_nop 0
	v_cndmask_b32_e32 v12, v220, v12, vcc
	v_cmp_le_i32_e32 vcc, v90, v126
	v_or_b32_e32 v90, 25, v0
	s_nop 0
	v_cndmask_b32_e32 v76, v220, v76, vcc
	v_cmp_le_i32_e32 vcc, v90, v126
	v_or_b32_e32 v90, 57, v0
	s_nop 0
	v_cndmask_b32_e32 v13, v220, v13, vcc
	v_cmp_le_i32_e32 vcc, v90, v126
	v_or_b32_e32 v90, 26, v0
	s_nop 0
	v_cndmask_b32_e32 v77, v220, v77, vcc
	v_cmp_le_i32_e32 vcc, v90, v126
	v_or_b32_e32 v90, 58, v0
	s_nop 0
	v_cndmask_b32_e32 v10, v220, v10, vcc
	v_cmp_le_i32_e32 vcc, v90, v126
	v_or_b32_e32 v90, 27, v0
	v_or_b32_e32 v0, 59, v0
	v_cndmask_b32_e32 v78, v220, v78, vcc
	v_cmp_le_i32_e32 vcc, v90, v126
	s_nop 1
	v_cndmask_b32_e32 v11, v220, v11, vcc
	v_cmp_le_i32_e32 vcc, v0, v126
	s_nop 1
	v_cndmask_b32_e32 v79, v220, v79, vcc
